# v33 + final phase: next token's rows/wts indices prefetched one iteration ahead so the dependent expert-output row loads issue at the loop top
# speedup vs baseline: 1.0062x; 1.0034x over previous
.LBB0_1409:
	s_or_b64 exec, exec, s[0:1]
	s_and_b64 vcc, exec, s[70:71]
	s_waitcnt lgkmcnt(0)
	s_barrier
	s_cbranch_vccz .LBB0_1412
	v_mbcnt_hi_u32_b32 v2, -1, v186
	v_and_b32_e32 v3, 64, v2
	v_add_u32_e32 v3, 64, v3
	v_xor_b32_e32 v4, 1, v2
	v_cmp_lt_i32_e32 vcc, v4, v3
	v_ashrrev_i32_e32 v161, 31, v160
	v_readlane_b32 s0, v234, 23
	v_cndmask_b32_e32 v4, v2, v4, vcc
	v_lshlrev_b32_e32 v12, 2, v4
	v_xor_b32_e32 v4, 2, v2
	v_cmp_lt_i32_e32 vcc, v4, v3
	v_readlane_b32 s1, v234, 24
	v_readlane_b32 s2, v234, 25
	v_cndmask_b32_e32 v4, v2, v4, vcc
	v_lshlrev_b32_e32 v13, 2, v4
	v_xor_b32_e32 v4, 4, v2
	v_cmp_lt_i32_e32 vcc, v4, v3
	v_readlane_b32 s3, v234, 26
	v_readlane_b32 s11, v234, 34
	v_cndmask_b32_e32 v4, v2, v4, vcc
	v_lshlrev_b32_e32 v14, 2, v4
	v_xor_b32_e32 v4, 8, v2
	v_cmp_lt_i32_e32 vcc, v4, v3
	s_ashr_i32 s47, s46, 31
	v_readlane_b32 s4, v234, 27
	v_cndmask_b32_e32 v4, v2, v4, vcc
	v_lshlrev_b32_e32 v15, 2, v4
	v_xor_b32_e32 v4, 16, v2
	v_cmp_lt_i32_e32 vcc, v4, v3
	v_readlane_b32 s14, v234, 37
	s_lshl_b32 s11, s82, 4
	v_cndmask_b32_e32 v4, v2, v4, vcc
	v_lshlrev_b32_e32 v16, 2, v4
	v_xor_b32_e32 v4, 32, v2
	v_cmp_lt_i32_e32 vcc, v4, v3
	v_readlane_b32 s5, v234, 28
	v_readlane_b32 s15, v234, 38
	v_cndmask_b32_e32 v2, v2, v4, vcc
	v_lshlrev_b32_e32 v17, 2, v2
	v_lshlrev_b64 v[2:3], 4, v[160:161]
	v_lshl_add_u64 v[4:5], s[0:1], 0, v[2:3]
	s_mov_b64 s[0:1], 0x1000
	v_lshl_add_u64 v[6:7], s[2:3], 0, v[2:3]
	v_lshl_add_u64 v[4:5], v[4:5], 0, s[0:1]
	v_lshl_add_u64 v[6:7], v[6:7], 0, s[0:1]
	v_readlane_b32 s0, v234, 0
	v_readlane_b32 s1, v234, 1
	s_lshl_b32 s0, s0, 4
	s_lshl_b32 s1, s86, 1
	s_add_i32 s2, s0, s1
	s_lshl_b64 s[0:1], s[46:47], 12
	s_add_u32 s4, s14, s0
	v_readlane_b32 s6, v234, 29
	v_readlane_b32 s7, v234, 30
	s_addc_u32 s5, s15, s1
	s_ashr_i32 s81, s80, 31
	v_readlane_b32 s8, v234, 31
	s_lshl_b64 s[6:7], s[80:81], 12
	v_readlane_b32 s9, v234, 32
	v_readlane_b32 s10, v234, 33
	v_readlane_b32 s12, v234, 35
	v_readlane_b32 s13, v234, 36
	s_add_u32 s8, s84, s0
	v_lshl_add_u64 v[0:1], v[160:161], 3, s[68:69]
	s_addc_u32 s9, s85, s1
	v_mov_b32_e32 v18, 0
	s_mov_b32 s12, 0x10400000
	s_mov_b32 s10, 0x3fb504f3
	v_mov_b32_e32 v19, 0x3727c5ac
	s_mov_b32 s13, 0xf800000
	v_mov_b32_e32 v20, 0x260
	global_load_dwordx4 v[100:103], v[4:5], off
	global_load_dwordx4 v[104:107], v[4:5], off offset:1024
	global_load_dwordx4 v[108:111], v[4:5], off offset:2048
	global_load_dwordx4 v[112:115], v[4:5], off offset:3072
	global_load_dwordx4 v[116:119], v[6:7], off
	global_load_dwordx4 v[120:123], v[6:7], off offset:1024
	global_load_dwordx4 v[124:127], v[6:7], off offset:2048
	global_load_dwordx4 v[128:131], v[6:7], off offset:3072
	s_waitcnt vmcnt(0)
	s_ashr_i32 s3, s2, 31
	s_lshl_b64 s[16:17], s[2:3], 2
	s_add_u32 s18, s50, s16
	s_addc_u32 s19, s51, s17
	s_add_u32 s16, s54, s16
	s_addc_u32 s17, s55, s17
	global_load_dwordx2 v[132:133], v18, s[18:19]
	global_load_dwordx2 v[134:135], v18, s[16:17]
	s_waitcnt vmcnt(0)
.LBB0_1411:
	v_lshl_add_u64 v[8:9], s[8:9], 0, v[2:3]
	v_add_co_u32_e32 v8, vcc, s12, v8
	s_nop 1
	v_addc_co_u32_e32 v9, vcc, 0, v9, vcc
	global_load_dwordx4 v[30:33], v[8:9], off nt
	global_load_dwordx4 v[34:37], v[8:9], off offset:1024 nt
	global_load_dwordx4 v[38:41], v[8:9], off offset:2048 nt
	global_load_dwordx4 v[42:45], v[8:9], off offset:3072 nt
	v_mov_b32_e32 v8, v132
	v_mov_b32_e32 v9, v133
	v_mov_b32_e32 v46, v134
	v_mov_b32_e32 v47, v135
	v_lshl_add_u64 v[10:11], s[4:5], 0, v[2:3]
	s_add_i32 s46, s46, s80
	s_add_i32 s2, s2, s11
	s_add_u32 s4, s4, s6
	s_addc_u32 s5, s5, s7
	s_add_u32 s8, s8, s6
	s_addc_u32 s9, s9, s7
	s_ashr_i32 s3, s2, 31
	s_lshl_b64 s[16:17], s[2:3], 2
	s_add_u32 s18, s50, s16
	s_addc_u32 s19, s51, s17
	s_add_u32 s16, s54, s16
	s_addc_u32 s17, s55, s17
	s_cmpk_lt_i32 s46, 0x4000
	s_cbranch_scc0 .Lfin_skip
	global_load_dwordx2 v[132:133], v18, s[18:19]
	global_load_dwordx2 v[134:135], v18, s[16:17]
.Lfin_skip:
	v_ashrrev_i32_e32 v49, 31, v8
	v_mov_b32_e32 v48, v8
	v_ashrrev_i32_e32 v51, 31, v9
	v_mov_b32_e32 v50, v9
	v_lshlrev_b64 v[8:9], 11, v[48:49]
	v_lshlrev_b64 v[48:49], 11, v[50:51]
	v_lshl_add_u64 v[8:9], v[0:1], 0, v[8:9]
	v_lshl_add_u64 v[48:49], v[0:1], 0, v[48:49]
	global_load_dwordx2 v[50:51], v[8:9], off nt
	global_load_dwordx2 v[52:53], v[48:49], off nt
	global_load_dwordx2 v[54:55], v[8:9], off offset:512 nt
	global_load_dwordx2 v[56:57], v[48:49], off offset:512 nt
	global_load_dwordx2 v[58:59], v[8:9], off offset:1024 nt
	global_load_dwordx2 v[60:61], v[48:49], off offset:1024 nt
	global_load_dwordx2 v[62:63], v[8:9], off offset:1536 nt
	global_load_dwordx2 v[64:65], v[48:49], off offset:1536 nt
	s_waitcnt vmcnt(7)
	v_lshlrev_b32_e32 v8, 16, v50
	v_and_b32_e32 v9, 0xffff0000, v50
	v_lshlrev_b32_e32 v48, 16, v51
	v_and_b32_e32 v49, 0xffff0000, v51
	s_waitcnt vmcnt(6)
	v_lshlrev_b32_e32 v50, 16, v52
	v_and_b32_e32 v51, 0xffff0000, v52
	v_lshlrev_b32_e32 v52, 16, v53
	v_and_b32_e32 v53, 0xffff0000, v53
	s_waitcnt vmcnt(4)
	v_lshlrev_b32_e32 v68, 16, v56
	v_and_b32_e32 v69, 0xffff0000, v56
	v_lshlrev_b32_e32 v56, 16, v57
	v_and_b32_e32 v57, 0xffff0000, v57
	v_lshlrev_b32_e32 v66, 16, v54
	v_and_b32_e32 v67, 0xffff0000, v54
	v_lshlrev_b32_e32 v54, 16, v55
	v_and_b32_e32 v55, 0xffff0000, v55
	s_waitcnt vmcnt(2)
	v_lshlrev_b32_e32 v72, 16, v60
	v_and_b32_e32 v73, 0xffff0000, v60
	v_lshlrev_b32_e32 v60, 16, v61
	v_and_b32_e32 v61, 0xffff0000, v61
	s_waitcnt vmcnt(0)
	v_lshlrev_b32_e32 v76, 16, v64
	v_and_b32_e32 v77, 0xffff0000, v64
	v_lshlrev_b32_e32 v64, 16, v65
	v_and_b32_e32 v65, 0xffff0000, v65
	v_pk_mul_f32 v[52:53], v[46:47], v[52:53] op_sel:[1,0]
	v_pk_mul_f32 v[50:51], v[46:47], v[50:51] op_sel:[1,0]
	v_pk_mul_f32 v[56:57], v[46:47], v[56:57] op_sel:[1,0]
	v_pk_mul_f32 v[68:69], v[46:47], v[68:69] op_sel:[1,0]
	v_lshlrev_b32_e32 v70, 16, v58
	v_and_b32_e32 v71, 0xffff0000, v58
	v_lshlrev_b32_e32 v58, 16, v59
	v_and_b32_e32 v59, 0xffff0000, v59
	v_lshlrev_b32_e32 v74, 16, v62
	v_and_b32_e32 v75, 0xffff0000, v62
	v_lshlrev_b32_e32 v62, 16, v63
	v_and_b32_e32 v63, 0xffff0000, v63
	v_pk_mul_f32 v[60:61], v[46:47], v[60:61] op_sel:[1,0]
	v_pk_mul_f32 v[72:73], v[46:47], v[72:73] op_sel:[1,0]
	v_pk_mul_f32 v[64:65], v[46:47], v[64:65] op_sel:[1,0]
	v_pk_mul_f32 v[76:77], v[46:47], v[76:77] op_sel:[1,0]
	v_pk_fma_f32 v[8:9], v[46:47], v[8:9], v[50:51] op_sel_hi:[0,1,1]
	v_pk_fma_f32 v[48:49], v[46:47], v[48:49], v[52:53] op_sel_hi:[0,1,1]
	v_pk_fma_f32 v[50:51], v[46:47], v[66:67], v[68:69] op_sel_hi:[0,1,1]
	v_pk_fma_f32 v[52:53], v[46:47], v[54:55], v[56:57] op_sel_hi:[0,1,1]
	v_pk_fma_f32 v[54:55], v[46:47], v[70:71], v[72:73] op_sel_hi:[0,1,1]
	v_pk_fma_f32 v[56:57], v[46:47], v[58:59], v[60:61] op_sel_hi:[0,1,1]
	v_pk_fma_f32 v[58:59], v[46:47], v[74:75], v[76:77] op_sel_hi:[0,1,1]
	v_pk_fma_f32 v[46:47], v[46:47], v[62:63], v[64:65] op_sel_hi:[0,1,1]
	v_pk_fma_f32 v[32:33], v[32:33], s[10:11], v[48:49] op_sel_hi:[1,0,1]
	v_pk_fma_f32 v[8:9], v[30:31], s[10:11], v[8:9] op_sel_hi:[1,0,1]
	v_pk_fma_f32 v[30:31], v[36:37], s[10:11], v[52:53] op_sel_hi:[1,0,1]
	v_pk_fma_f32 v[34:35], v[34:35], s[10:11], v[50:51] op_sel_hi:[1,0,1]
	v_pk_fma_f32 v[36:37], v[40:41], s[10:11], v[56:57] op_sel_hi:[1,0,1]
	v_pk_fma_f32 v[40:41], v[44:45], s[10:11], v[46:47] op_sel_hi:[1,0,1]
	v_pk_mov_b32 v[44:45], v[8:9], v[32:33] op_sel:[1,0]
	v_mov_b32_e32 v46, v8
	v_mov_b32_e32 v47, v33
	v_pk_mov_b32 v[48:49], v[34:35], v[30:31] op_sel:[1,0]
	v_mov_b32_e32 v50, v34
	v_mov_b32_e32 v51, v31
	v_pk_add_f32 v[44:45], v[44:45], v[46:47]
	v_pk_add_f32 v[46:47], v[48:49], v[50:51]
	v_pk_fma_f32 v[38:39], v[38:39], s[10:11], v[54:55] op_sel_hi:[1,0,1]
	v_pk_fma_f32 v[42:43], v[42:43], s[10:11], v[58:59] op_sel_hi:[1,0,1]
	v_add_f32_e32 v21, v44, v45
	v_pk_add_f32 v[44:45], v[46:47], v[46:47] op_sel:[0,1] op_sel_hi:[1,0]
	v_add_f32_e32 v52, v38, v39
	v_add_f32_e32 v54, v36, v37
	v_mov_b32_e32 v57, v42
	v_mov_b32_e32 v53, v40
	v_mov_b32_e32 v55, v41
	v_add_f32_e32 v56, 0, v21
	v_mov_b32_e32 v45, v43
	v_pk_add_f32 v[48:49], v[52:53], v[54:55]
	v_pk_add_f32 v[44:45], v[56:57], v[44:45]
	s_nop 0
	v_pk_add_f32 v[44:45], v[44:45], v[48:49]
	s_nop 0
	v_add_f32_e32 v21, v44, v45
	ds_bpermute_b32 v44, v12, v21
	s_waitcnt lgkmcnt(0)
	v_add_f32_e32 v21, v21, v44
	ds_bpermute_b32 v44, v13, v21
	s_waitcnt lgkmcnt(0)
	v_add_f32_e32 v21, v21, v44
	ds_bpermute_b32 v44, v14, v21
	s_waitcnt lgkmcnt(0)
	v_add_f32_e32 v21, v21, v44
	ds_bpermute_b32 v44, v15, v21
	s_waitcnt lgkmcnt(0)
	v_add_f32_e32 v21, v21, v44
	ds_bpermute_b32 v44, v16, v21
	s_waitcnt lgkmcnt(0)
	v_add_f32_e32 v21, v21, v44
	ds_bpermute_b32 v44, v17, v21
	s_waitcnt lgkmcnt(0)
	v_add_f32_e32 v21, v21, v44
	v_fmamk_f32 v9, v21, 0xba800000, v9
	v_fmac_f32_e32 v8, 0xba800000, v21
	v_fmamk_f32 v33, v21, 0xba800000, v33
	v_fmac_f32_e32 v32, 0xba800000, v21
	v_fmamk_f32 v35, v21, 0xba800000, v35
	v_fmac_f32_e32 v34, 0xba800000, v21
	v_fmamk_f32 v31, v21, 0xba800000, v31
	v_fmac_f32_e32 v30, 0xba800000, v21
	v_pk_mul_f32 v[44:45], v[32:33], v[32:33]
	v_pk_mul_f32 v[46:47], v[8:9], v[8:9]
	v_pk_mul_f32 v[48:49], v[30:31], v[30:31]
	v_pk_mul_f32 v[50:51], v[34:35], v[34:35]
	v_fmac_f32_e32 v38, 0xba800000, v21
	v_fmac_f32_e32 v36, 0xba800000, v21
	v_pk_mov_b32 v[56:57], v[46:47], v[44:45] op_sel:[1,0]
	v_mov_b32_e32 v47, v45
	v_pk_mov_b32 v[44:45], v[50:51], v[48:49] op_sel:[1,0]
	v_mov_b32_e32 v51, v49
	v_fmamk_f32 v39, v21, 0xba800000, v39
	v_fmamk_f32 v37, v21, 0xba800000, v37
	v_mul_f32_e32 v52, v38, v38
	v_mul_f32_e32 v54, v36, v36
	v_pk_add_f32 v[46:47], v[56:57], v[46:47]
	v_pk_add_f32 v[44:45], v[44:45], v[50:51]
	v_fmamk_f32 v41, v21, 0xba800000, v41
	v_fmac_f32_e32 v40, 0xba800000, v21
	v_fmamk_f32 v43, v21, 0xba800000, v43
	v_fmac_f32_e32 v42, 0xba800000, v21
	v_pk_fma_f32 v[48:49], v[38:39], v[38:39], v[52:53] op_sel_hi:[1,1,0]
	v_pk_fma_f32 v[52:53], v[36:37], v[36:37], v[54:55] op_sel_hi:[1,1,0]
	v_pk_add_f32 v[46:47], v[46:47], v[46:47] op_sel_hi:[0,1]
	v_pk_add_f32 v[44:45], v[44:45], v[44:45] op_sel_hi:[0,1]
	v_mul_f32_e32 v48, v42, v42
	v_mul_f32_e32 v52, v43, v43
	v_mul_f32_e32 v46, v40, v40
	v_mul_f32_e32 v44, v41, v41
	v_pk_add_f32 v[48:49], v[48:49], v[52:53]
	v_pk_add_f32 v[44:45], v[46:47], v[44:45]
	s_nop 0
	v_pk_add_f32 v[44:45], v[48:49], v[44:45]
	s_nop 0
	v_add_f32_e32 v21, v44, v45
	ds_bpermute_b32 v44, v12, v21
	s_waitcnt lgkmcnt(0)
	v_add_f32_e32 v21, v21, v44
	ds_bpermute_b32 v44, v13, v21
	s_waitcnt lgkmcnt(0)
	v_add_f32_e32 v21, v21, v44
	ds_bpermute_b32 v44, v14, v21
	s_waitcnt lgkmcnt(0)
	v_add_f32_e32 v21, v21, v44
	ds_bpermute_b32 v44, v15, v21
	s_waitcnt lgkmcnt(0)
	v_add_f32_e32 v21, v21, v44
	ds_bpermute_b32 v44, v16, v21
	s_waitcnt lgkmcnt(0)
	v_add_f32_e32 v21, v21, v44
	ds_bpermute_b32 v44, v17, v21
	s_waitcnt lgkmcnt(0)
	v_add_f32_e32 v21, v21, v44
	v_fmamk_f32 v21, v21, 0x3a800000, v19
	v_mul_f32_e32 v44, 0x4f800000, v21
	v_cmp_gt_f32_e32 vcc, s13, v21
	s_nop 1
	v_cndmask_b32_e32 v21, v21, v44, vcc
	v_sqrt_f32_e32 v44, v21
	s_nop 0
	v_add_u32_e32 v45, -1, v44
	v_add_u32_e32 v46, 1, v44
	v_fma_f32 v47, -v45, v44, v21
	v_fma_f32 v48, -v46, v44, v21
	v_cmp_ge_f32_e64 s[0:1], 0, v47
	s_nop 1
	v_cndmask_b32_e64 v44, v44, v45, s[0:1]
	v_cmp_lt_f32_e64 s[0:1], 0, v48
	s_nop 1
	v_cndmask_b32_e64 v44, v44, v46, s[0:1]
	v_mul_f32_e32 v45, 0x37800000, v44
	v_cndmask_b32_e32 v44, v44, v45, vcc
	v_cmp_class_f32_e32 vcc, v21, v20
	s_nop 1
	v_cndmask_b32_e32 v21, v44, v21, vcc
	v_div_scale_f32 v44, s[0:1], v21, v21, 1.0
	v_rcp_f32_e32 v46, v44
	v_div_scale_f32 v45, vcc, 1.0, v21, 1.0
	v_fma_f32 v47, -v44, v46, 1.0
	v_fmac_f32_e32 v46, v47, v46
	v_mul_f32_e32 v47, v45, v46
	v_fma_f32 v48, -v44, v47, v45
	v_fmac_f32_e32 v47, v48, v46
	v_fma_f32 v44, -v44, v47, v45
	v_div_fmas_f32 v44, v44, v46, v47
	v_div_fixup_f32 v44, v44, v21, 1.0
	v_pk_mul_f32 v[8:9], v[8:9], v[44:45] op_sel_hi:[1,0]
	v_pk_mul_f32 v[32:33], v[32:33], v[44:45] op_sel_hi:[1,0]
	v_pk_fma_f32 v[22:23], v[100:101], v[8:9], v[116:117]
	v_pk_fma_f32 v[24:25], v[102:103], v[32:33], v[118:119]
	global_store_dwordx4 v[10:11], v[22:25], off nt
	s_nop 0
	v_pk_mul_f32 v[8:9], v[30:31], v[44:45] op_sel_hi:[1,0]
	v_pk_mul_f32 v[30:31], v[34:35], v[44:45] op_sel_hi:[1,0]
	v_pk_fma_f32 v[24:25], v[106:107], v[8:9], v[122:123]
	v_pk_fma_f32 v[22:23], v[104:105], v[30:31], v[120:121]
	global_store_dwordx4 v[10:11], v[22:25], off offset:1024 nt
	s_nop 0
	v_pk_mul_f32 v[8:9], v[36:37], v[44:45] op_sel_hi:[1,0]
	v_pk_mul_f32 v[30:31], v[38:39], v[44:45] op_sel_hi:[1,0]
	v_pk_fma_f32 v[24:25], v[110:111], v[8:9], v[126:127]
	v_pk_fma_f32 v[22:23], v[108:109], v[30:31], v[124:125]
	global_store_dwordx4 v[10:11], v[22:25], off offset:2048 nt
	s_nop 0
	v_pk_mul_f32 v[8:9], v[40:41], v[44:45] op_sel_hi:[1,0]
	v_pk_mul_f32 v[30:31], v[42:43], v[44:45] op_sel_hi:[1,0]
	v_pk_fma_f32 v[24:25], v[114:115], v[8:9], v[130:131]
	v_pk_fma_f32 v[22:23], v[112:113], v[30:31], v[128:129]
	global_store_dwordx4 v[10:11], v[22:25], off offset:3072 nt
	s_cbranch_scc1 .LBB0_1411
